# v54 + sample task window rows touched during the top-k and bg load issued with the G loads, P2 k4-loop stream hook skips while its chunk is in flight
# speedup vs baseline: 1.0118x; 1.0021x over previous
; __device__ __forceinline__ int crow(int r, int hi) { return (r & 3) + 8 * (r >> 2) + 4 * hi; }
; __device__ __forceinline__ void sample_task(const Prm& P, Ctx& C, int task) {
;     ...
;         if (C.wave == 0) {
;             if (slot == ts) { const float gate = ((const float*)(P.ws + WS_G))[row * 24 + head * 3 + 0];
; #pragma unroll
;                 for (int dblk = 0; dblk < 2; ++dblk)
; #pragma unroll
;                     for (int r = 0; r < 16; ++r) ocs[g * 64 + 32 * dblk + crow(r, hi)] = oacc[(dblk * 16 + r) * 64 + lane] * gate; }
.Locs_w:
	v_readlane_b32 s2, v250, 20
	v_readlane_b32 s3, v250, 21
	v_readlane_b32 s4, v253, 28
	v_readlane_b32 s5, v253, 29
	s_add_u32 s2, s2, s4
	s_addc_u32 s3, s3, s5
	v_readlane_b32 s4, v251, 55
	s_lshl_b32 s4, s4, 10
	s_add_u32 s2, s2, s4
	s_addc_u32 s3, s3, 0
	s_lshl_b32 s4, s33, 2
	s_add_u32 s2, s2, s4
	s_addc_u32 s3, s3, 0
	v_mbcnt_lo_u32_b32 v234, -1, 0
	v_mbcnt_hi_u32_b32 v234, -1, v234
	v_lshlrev_b32_e32 v234, 10, v234
	global_load_dword v236, v234, s[2:3]
	global_load_dword v237, v234, s[2:3] offset:128
	global_load_dword v238, v234, s[2:3] offset:512
	global_load_dword v239, v234, s[2:3] offset:640
	v_readlane_b32 s0, v251, 55
	s_cmp_lg_u32 s0, 64
	s_cbranch_scc1 .LBB0_1555
	v_readlane_b32 s0, v251, 2
	s_nop 1
	v_cmp_eq_u32_e32 vcc, s0, v173
	s_and_saveexec_b64 s[0:1], vcc
	s_cbranch_execz .Locs_done
	s_mul_i32 s2, s81, 0x60
	s_mul_hi_u32 s3, s80, 0x60
	s_add_i32 s3, s3, s2
	s_mul_i32 s2, s80, 0x60
	v_readlane_b32 s4, v251, 21
	v_mul_u32_u24_e32 v0, 3, v172
	s_add_u32 s2, s4, s2
	v_readlane_b32 s4, v251, 22
	s_addc_u32 s3, s4, s3
	v_lshlrev_b32_e32 v0, 2, v0
	global_load_dword v0, v0, s[2:3]
	v_add_u32_e32 v20, 0x12000, v183
	v_add_u32_e32 v21, 0x1a000, v183
	ds_read_b32 v4, v20 offset:8192
	ds_read_b32 v5, v20 offset:8448
	ds_read_b32 v6, v20 offset:8704
	ds_read_b32 v7, v20 offset:8960
	ds_read_b32 v8, v20 offset:9216
	ds_read_b32 v9, v20 offset:9472
	ds_read_b32 v10, v20 offset:9728
	ds_read_b32 v11, v20 offset:9984
	ds_read_b32 v12, v20 offset:16384
	ds_read_b32 v13, v20 offset:16640
	ds_read_b32 v14, v20 offset:16896
	ds_read_b32 v15, v20 offset:17152
	ds_read_b32 v16, v20 offset:17408
	ds_read_b32 v17, v20 offset:17664
	ds_read_b32 v18, v20 offset:17920
	ds_read_b32 v19, v20 offset:18176
	s_waitcnt lgkmcnt(0)
	v_add_f32_e32 v4, v4, v12
	v_add_f32_e32 v5, v5, v13
	v_add_f32_e32 v6, v6, v14
	v_add_f32_e32 v7, v7, v15
	v_add_f32_e32 v8, v8, v16
	v_add_f32_e32 v9, v9, v17
	v_add_f32_e32 v10, v10, v18
	v_add_f32_e32 v11, v11, v19
	ds_read_b32 v12, v20 offset:24576
	ds_read_b32 v13, v20 offset:24832
	ds_read_b32 v14, v20 offset:25088
	ds_read_b32 v15, v20 offset:25344
	ds_read_b32 v16, v20 offset:25600
	ds_read_b32 v17, v20 offset:25856
	ds_read_b32 v18, v20 offset:26112
	ds_read_b32 v19, v20 offset:26368
	s_waitcnt lgkmcnt(0)
	v_add_f32_e32 v4, v4, v12
	v_add_f32_e32 v5, v5, v13
	v_add_f32_e32 v6, v6, v14
	v_add_f32_e32 v7, v7, v15
	v_add_f32_e32 v8, v8, v16
	v_add_f32_e32 v9, v9, v17
	v_add_f32_e32 v10, v10, v18
	v_add_f32_e32 v11, v11, v19
	ds_read_b32 v12, v20 offset:32768
	ds_read_b32 v13, v20 offset:33024
	ds_read_b32 v14, v20 offset:33280
	ds_read_b32 v15, v20 offset:33536
	ds_read_b32 v16, v20 offset:33792
	ds_read_b32 v17, v20 offset:34048
	ds_read_b32 v18, v20 offset:34304
	ds_read_b32 v19, v20 offset:34560
	s_waitcnt lgkmcnt(0)
	v_add_f32_e32 v4, v4, v12
	v_add_f32_e32 v5, v5, v13
	v_add_f32_e32 v6, v6, v14
	v_add_f32_e32 v7, v7, v15
	v_add_f32_e32 v8, v8, v16
	v_add_f32_e32 v9, v9, v17
	v_add_f32_e32 v10, v10, v18
	v_add_f32_e32 v11, v11, v19
	ds_read_b32 v12, v21 offset:8192
	ds_read_b32 v13, v21 offset:8448
	ds_read_b32 v14, v21 offset:8704
	ds_read_b32 v15, v21 offset:8960
	ds_read_b32 v16, v21 offset:9216
	ds_read_b32 v17, v21 offset:9472
	ds_read_b32 v18, v21 offset:9728
	ds_read_b32 v19, v21 offset:9984
	s_waitcnt lgkmcnt(0)
	v_add_f32_e32 v4, v4, v12
	v_add_f32_e32 v5, v5, v13
	v_add_f32_e32 v6, v6, v14
	v_add_f32_e32 v7, v7, v15
	v_add_f32_e32 v8, v8, v16
	v_add_f32_e32 v9, v9, v17
	v_add_f32_e32 v10, v10, v18
	v_add_f32_e32 v11, v11, v19
	ds_read_b32 v12, v21 offset:16384
	ds_read_b32 v13, v21 offset:16640
	ds_read_b32 v14, v21 offset:16896
	ds_read_b32 v15, v21 offset:17152
	ds_read_b32 v16, v21 offset:17408
	ds_read_b32 v17, v21 offset:17664
	ds_read_b32 v18, v21 offset:17920
	ds_read_b32 v19, v21 offset:18176
	s_waitcnt lgkmcnt(0)
	v_add_f32_e32 v4, v4, v12
	v_add_f32_e32 v5, v5, v13
	v_add_f32_e32 v6, v6, v14
	v_add_f32_e32 v7, v7, v15
	v_add_f32_e32 v8, v8, v16
	v_add_f32_e32 v9, v9, v17
	v_add_f32_e32 v10, v10, v18
	v_add_f32_e32 v11, v11, v19
	ds_read_b32 v12, v21 offset:24576
	ds_read_b32 v13, v21 offset:24832
	ds_read_b32 v14, v21 offset:25088
	ds_read_b32 v15, v21 offset:25344
	ds_read_b32 v16, v21 offset:25600
	ds_read_b32 v17, v21 offset:25856
	ds_read_b32 v18, v21 offset:26112
	ds_read_b32 v19, v21 offset:26368
	s_waitcnt lgkmcnt(0)
	v_add_f32_e32 v4, v4, v12
	v_add_f32_e32 v5, v5, v13
	v_add_f32_e32 v6, v6, v14
	v_add_f32_e32 v7, v7, v15
	v_add_f32_e32 v8, v8, v16
	v_add_f32_e32 v9, v9, v17
	v_add_f32_e32 v10, v10, v18
	v_add_f32_e32 v11, v11, v19
	ds_read_b32 v12, v21 offset:32768
	ds_read_b32 v13, v21 offset:33024
	ds_read_b32 v14, v21 offset:33280
	ds_read_b32 v15, v21 offset:33536
	ds_read_b32 v16, v21 offset:33792
	ds_read_b32 v17, v21 offset:34048
	ds_read_b32 v18, v21 offset:34304
	ds_read_b32 v19, v21 offset:34560
	s_waitcnt lgkmcnt(0)
	v_add_f32_e32 v4, v4, v12
	v_add_f32_e32 v5, v5, v13
	v_add_f32_e32 v6, v6, v14
	v_add_f32_e32 v7, v7, v15
	v_add_f32_e32 v8, v8, v16
	v_add_f32_e32 v9, v9, v17
	v_add_f32_e32 v10, v10, v18
	v_add_f32_e32 v11, v11, v19
	s_waitcnt vmcnt(0)
; __device__ __forceinline__ int crow(int r, int hi) { return (r & 3) + 8 * (r >> 2) + 4 * hi; }
; __device__ __forceinline__ void sample_task(const Prm& P, Ctx& C, int task) {
;     ...
;         if (C.wave == 0) {
;             if (slot == ts) { const float gate = ((const float*)(P.ws + WS_G))[row * 24 + head * 3 + 0];
; #pragma unroll
;                 for (int dblk = 0; dblk < 2; ++dblk)
; #pragma unroll
;                     for (int r = 0; r < 16; ++r) ocs[g * 64 + 32 * dblk + crow(r, hi)] = oacc[(dblk * 16 + r) * 64 + lane] * gate; }
	v_mul_f32_e32 v4, v0, v4
	v_mul_f32_e32 v5, v0, v5
	v_mul_f32_e32 v6, v0, v6
	v_mul_f32_e32 v7, v0, v7
	v_mul_f32_e32 v8, v0, v8
	v_mul_f32_e32 v9, v0, v9
	v_mul_f32_e32 v10, v0, v10
	v_mul_f32_e32 v11, v0, v11
	ds_write_b32 v199, v4 offset:0
	ds_write_b32 v199, v5 offset:4
	ds_write_b32 v199, v6 offset:8
	ds_write_b32 v199, v7 offset:12
	ds_write_b32 v199, v8 offset:32
	ds_write_b32 v199, v9 offset:36
	ds_write_b32 v199, v10 offset:40
	ds_write_b32 v199, v11 offset:44
	ds_read_b32 v4, v20 offset:10240
	ds_read_b32 v5, v20 offset:10496
	ds_read_b32 v6, v20 offset:10752
	ds_read_b32 v7, v20 offset:11008
	ds_read_b32 v8, v20 offset:11264
	ds_read_b32 v9, v20 offset:11520
	ds_read_b32 v10, v20 offset:11776
	ds_read_b32 v11, v20 offset:12032
	ds_read_b32 v12, v20 offset:18432
	ds_read_b32 v13, v20 offset:18688
	ds_read_b32 v14, v20 offset:18944
	ds_read_b32 v15, v20 offset:19200
	ds_read_b32 v16, v20 offset:19456
	ds_read_b32 v17, v20 offset:19712
	ds_read_b32 v18, v20 offset:19968
	ds_read_b32 v19, v20 offset:20224
	s_waitcnt lgkmcnt(0)
	v_add_f32_e32 v4, v4, v12
	v_add_f32_e32 v5, v5, v13
	v_add_f32_e32 v6, v6, v14
	v_add_f32_e32 v7, v7, v15
	v_add_f32_e32 v8, v8, v16
	v_add_f32_e32 v9, v9, v17
	v_add_f32_e32 v10, v10, v18
	v_add_f32_e32 v11, v11, v19
	ds_read_b32 v12, v20 offset:26624
	ds_read_b32 v13, v20 offset:26880
	ds_read_b32 v14, v20 offset:27136
	ds_read_b32 v15, v20 offset:27392
	ds_read_b32 v16, v20 offset:27648
	ds_read_b32 v17, v20 offset:27904
	ds_read_b32 v18, v20 offset:28160
	ds_read_b32 v19, v20 offset:28416
	s_waitcnt lgkmcnt(0)
	v_add_f32_e32 v4, v4, v12
	v_add_f32_e32 v5, v5, v13
	v_add_f32_e32 v6, v6, v14
	v_add_f32_e32 v7, v7, v15
	v_add_f32_e32 v8, v8, v16
	v_add_f32_e32 v9, v9, v17
	v_add_f32_e32 v10, v10, v18
	v_add_f32_e32 v11, v11, v19
	ds_read_b32 v12, v20 offset:34816
	ds_read_b32 v13, v20 offset:35072
	ds_read_b32 v14, v20 offset:35328
	ds_read_b32 v15, v20 offset:35584
	ds_read_b32 v16, v20 offset:35840
	ds_read_b32 v17, v20 offset:36096
	ds_read_b32 v18, v20 offset:36352
	ds_read_b32 v19, v20 offset:36608
	s_waitcnt lgkmcnt(0)
	v_add_f32_e32 v4, v4, v12
	v_add_f32_e32 v5, v5, v13
	v_add_f32_e32 v6, v6, v14
	v_add_f32_e32 v7, v7, v15
	v_add_f32_e32 v8, v8, v16
	v_add_f32_e32 v9, v9, v17
	v_add_f32_e32 v10, v10, v18
	v_add_f32_e32 v11, v11, v19
	ds_read_b32 v12, v21 offset:10240
	ds_read_b32 v13, v21 offset:10496
	ds_read_b32 v14, v21 offset:10752
	ds_read_b32 v15, v21 offset:11008
	ds_read_b32 v16, v21 offset:11264
	ds_read_b32 v17, v21 offset:11520
	ds_read_b32 v18, v21 offset:11776
	ds_read_b32 v19, v21 offset:12032
	s_waitcnt lgkmcnt(0)
	v_add_f32_e32 v4, v4, v12
	v_add_f32_e32 v5, v5, v13
	v_add_f32_e32 v6, v6, v14
	v_add_f32_e32 v7, v7, v15
	v_add_f32_e32 v8, v8, v16
	v_add_f32_e32 v9, v9, v17
	v_add_f32_e32 v10, v10, v18
	v_add_f32_e32 v11, v11, v19
	ds_read_b32 v12, v21 offset:18432
	ds_read_b32 v13, v21 offset:18688
	ds_read_b32 v14, v21 offset:18944
	ds_read_b32 v15, v21 offset:19200
	ds_read_b32 v16, v21 offset:19456
	ds_read_b32 v17, v21 offset:19712
	ds_read_b32 v18, v21 offset:19968
	ds_read_b32 v19, v21 offset:20224
	s_waitcnt lgkmcnt(0)
	v_add_f32_e32 v4, v4, v12
	v_add_f32_e32 v5, v5, v13
	v_add_f32_e32 v6, v6, v14
	v_add_f32_e32 v7, v7, v15
	v_add_f32_e32 v8, v8, v16
	v_add_f32_e32 v9, v9, v17
	v_add_f32_e32 v10, v10, v18
	v_add_f32_e32 v11, v11, v19
	ds_read_b32 v12, v21 offset:26624
	ds_read_b32 v13, v21 offset:26880
	ds_read_b32 v14, v21 offset:27136
	ds_read_b32 v15, v21 offset:27392
	ds_read_b32 v16, v21 offset:27648
	ds_read_b32 v17, v21 offset:27904
	ds_read_b32 v18, v21 offset:28160
	ds_read_b32 v19, v21 offset:28416
	s_waitcnt lgkmcnt(0)
	v_add_f32_e32 v4, v4, v12
	v_add_f32_e32 v5, v5, v13
	v_add_f32_e32 v6, v6, v14
	v_add_f32_e32 v7, v7, v15
	v_add_f32_e32 v8, v8, v16
	v_add_f32_e32 v9, v9, v17
	v_add_f32_e32 v10, v10, v18
	v_add_f32_e32 v11, v11, v19
	ds_read_b32 v12, v21 offset:34816
	ds_read_b32 v13, v21 offset:35072
	ds_read_b32 v14, v21 offset:35328
	ds_read_b32 v15, v21 offset:35584
	ds_read_b32 v16, v21 offset:35840
	ds_read_b32 v17, v21 offset:36096
	ds_read_b32 v18, v21 offset:36352
	ds_read_b32 v19, v21 offset:36608
	s_waitcnt lgkmcnt(0)
	v_add_f32_e32 v4, v4, v12
	v_add_f32_e32 v5, v5, v13
	v_add_f32_e32 v6, v6, v14
	v_add_f32_e32 v7, v7, v15
	v_add_f32_e32 v8, v8, v16
	v_add_f32_e32 v9, v9, v17
	v_add_f32_e32 v10, v10, v18
	v_add_f32_e32 v11, v11, v19
	v_mul_f32_e32 v4, v0, v4
	v_mul_f32_e32 v5, v0, v5
	v_mul_f32_e32 v6, v0, v6
	v_mul_f32_e32 v7, v0, v7
	v_mul_f32_e32 v8, v0, v8
	v_mul_f32_e32 v9, v0, v9
	v_mul_f32_e32 v10, v0, v10
	v_mul_f32_e32 v11, v0, v11
	ds_write_b32 v199, v4 offset:64
	ds_write_b32 v199, v5 offset:68
	ds_write_b32 v199, v6 offset:72
	ds_write_b32 v199, v7 offset:76
	ds_write_b32 v199, v8 offset:96
	ds_write_b32 v199, v9 offset:100
	ds_write_b32 v199, v10 offset:104
	ds_write_b32 v199, v11 offset:108
	ds_read_b32 v4, v20 offset:12288
	ds_read_b32 v5, v20 offset:12544
	ds_read_b32 v6, v20 offset:12800
	ds_read_b32 v7, v20 offset:13056
	ds_read_b32 v8, v20 offset:13312
	ds_read_b32 v9, v20 offset:13568
	ds_read_b32 v10, v20 offset:13824
	ds_read_b32 v11, v20 offset:14080
	ds_read_b32 v12, v20 offset:20480
	ds_read_b32 v13, v20 offset:20736
	ds_read_b32 v14, v20 offset:20992
	ds_read_b32 v15, v20 offset:21248
	ds_read_b32 v16, v20 offset:21504
	ds_read_b32 v17, v20 offset:21760
	ds_read_b32 v18, v20 offset:22016
	ds_read_b32 v19, v20 offset:22272
	s_waitcnt lgkmcnt(0)
; __device__ __forceinline__ int crow(int r, int hi) { return (r & 3) + 8 * (r >> 2) + 4 * hi; }
; __device__ __forceinline__ void sample_task(const Prm& P, Ctx& C, int task) {
;     ...
; #pragma unroll
;         for (int dblk = 0; dblk < 2; ++dblk)
; #pragma unroll
;             for (int r = 0; r < 16; ++r) atomicAdd((float*)(oacc + (dblk * 16 + r) * 64 + lane), o[dblk][r]);
;         __syncthreads();
;         if (C.wave == 0) {
;             if (slot == ts) { const float gate = ((const float*)(P.ws + WS_G))[row * 24 + head * 3 + 0];
; #pragma unroll
;                 for (int dblk = 0; dblk < 2; ++dblk)
; #pragma unroll
;                     for (int r = 0; r < 16; ++r) ocs[g * 64 + 32 * dblk + crow(r, hi)] = oacc[(dblk * 16 + r) * 64 + lane] * gate; }
	v_add_f32_e32 v4, v4, v12
	v_add_f32_e32 v5, v5, v13
	v_add_f32_e32 v6, v6, v14
	v_add_f32_e32 v7, v7, v15
	v_add_f32_e32 v8, v8, v16
	v_add_f32_e32 v9, v9, v17
	v_add_f32_e32 v10, v10, v18
	v_add_f32_e32 v11, v11, v19
	ds_read_b32 v12, v20 offset:28672
	ds_read_b32 v13, v20 offset:28928
	ds_read_b32 v14, v20 offset:29184
	ds_read_b32 v15, v20 offset:29440
	ds_read_b32 v16, v20 offset:29696
	ds_read_b32 v17, v20 offset:29952
	ds_read_b32 v18, v20 offset:30208
	ds_read_b32 v19, v20 offset:30464
	s_waitcnt lgkmcnt(0)
	v_add_f32_e32 v4, v4, v12
	v_add_f32_e32 v5, v5, v13
	v_add_f32_e32 v6, v6, v14
	v_add_f32_e32 v7, v7, v15
	v_add_f32_e32 v8, v8, v16
	v_add_f32_e32 v9, v9, v17
	v_add_f32_e32 v10, v10, v18
	v_add_f32_e32 v11, v11, v19
	ds_read_b32 v12, v20 offset:36864
	ds_read_b32 v13, v20 offset:37120
	ds_read_b32 v14, v20 offset:37376
	ds_read_b32 v15, v20 offset:37632
	ds_read_b32 v16, v20 offset:37888
	ds_read_b32 v17, v20 offset:38144
	ds_read_b32 v18, v20 offset:38400
	ds_read_b32 v19, v20 offset:38656
	s_waitcnt lgkmcnt(0)
	v_add_f32_e32 v4, v4, v12
	v_add_f32_e32 v5, v5, v13
	v_add_f32_e32 v6, v6, v14
	v_add_f32_e32 v7, v7, v15
	v_add_f32_e32 v8, v8, v16
	v_add_f32_e32 v9, v9, v17
	v_add_f32_e32 v10, v10, v18
	v_add_f32_e32 v11, v11, v19
	ds_read_b32 v12, v21 offset:12288
	ds_read_b32 v13, v21 offset:12544
	ds_read_b32 v14, v21 offset:12800
	ds_read_b32 v15, v21 offset:13056
	ds_read_b32 v16, v21 offset:13312
	ds_read_b32 v17, v21 offset:13568
	ds_read_b32 v18, v21 offset:13824
	ds_read_b32 v19, v21 offset:14080
	s_waitcnt lgkmcnt(0)
	v_add_f32_e32 v4, v4, v12
	v_add_f32_e32 v5, v5, v13
	v_add_f32_e32 v6, v6, v14
	v_add_f32_e32 v7, v7, v15
	v_add_f32_e32 v8, v8, v16
	v_add_f32_e32 v9, v9, v17
	v_add_f32_e32 v10, v10, v18
	v_add_f32_e32 v11, v11, v19
	ds_read_b32 v12, v21 offset:20480
	ds_read_b32 v13, v21 offset:20736
	ds_read_b32 v14, v21 offset:20992
	ds_read_b32 v15, v21 offset:21248
	ds_read_b32 v16, v21 offset:21504
	ds_read_b32 v17, v21 offset:21760
	ds_read_b32 v18, v21 offset:22016
	ds_read_b32 v19, v21 offset:22272
	s_waitcnt lgkmcnt(0)
	v_add_f32_e32 v4, v4, v12
	v_add_f32_e32 v5, v5, v13
	v_add_f32_e32 v6, v6, v14
	v_add_f32_e32 v7, v7, v15
	v_add_f32_e32 v8, v8, v16
	v_add_f32_e32 v9, v9, v17
	v_add_f32_e32 v10, v10, v18
	v_add_f32_e32 v11, v11, v19
	ds_read_b32 v12, v21 offset:28672
	ds_read_b32 v13, v21 offset:28928
	ds_read_b32 v14, v21 offset:29184
	ds_read_b32 v15, v21 offset:29440
	ds_read_b32 v16, v21 offset:29696
	ds_read_b32 v17, v21 offset:29952
	ds_read_b32 v18, v21 offset:30208
	ds_read_b32 v19, v21 offset:30464
	s_waitcnt lgkmcnt(0)
	v_add_f32_e32 v4, v4, v12
	v_add_f32_e32 v5, v5, v13
	v_add_f32_e32 v6, v6, v14
	v_add_f32_e32 v7, v7, v15
	v_add_f32_e32 v8, v8, v16
	v_add_f32_e32 v9, v9, v17
	v_add_f32_e32 v10, v10, v18
	v_add_f32_e32 v11, v11, v19
	ds_read_b32 v12, v21 offset:36864
	ds_read_b32 v13, v21 offset:37120
	ds_read_b32 v14, v21 offset:37376
	ds_read_b32 v15, v21 offset:37632
	ds_read_b32 v16, v21 offset:37888
	ds_read_b32 v17, v21 offset:38144
	ds_read_b32 v18, v21 offset:38400
	ds_read_b32 v19, v21 offset:38656
	s_waitcnt lgkmcnt(0)
	v_add_f32_e32 v4, v4, v12
	v_add_f32_e32 v5, v5, v13
	v_add_f32_e32 v6, v6, v14
	v_add_f32_e32 v7, v7, v15
	v_add_f32_e32 v8, v8, v16
	v_add_f32_e32 v9, v9, v17
	v_add_f32_e32 v10, v10, v18
	v_add_f32_e32 v11, v11, v19
	v_mul_f32_e32 v4, v0, v4
	v_mul_f32_e32 v5, v0, v5
	v_mul_f32_e32 v6, v0, v6
	v_mul_f32_e32 v7, v0, v7
	v_mul_f32_e32 v8, v0, v8
	v_mul_f32_e32 v9, v0, v9
	v_mul_f32_e32 v10, v0, v10
	v_mul_f32_e32 v11, v0, v11
	ds_write_b32 v199, v4 offset:128
	ds_write_b32 v199, v5 offset:132
	ds_write_b32 v199, v6 offset:136
	ds_write_b32 v199, v7 offset:140
	ds_write_b32 v199, v8 offset:160
	ds_write_b32 v199, v9 offset:164
	ds_write_b32 v199, v10 offset:168
	ds_write_b32 v199, v11 offset:172
	ds_read_b32 v4, v20 offset:14336
	ds_read_b32 v5, v20 offset:14592
	ds_read_b32 v6, v20 offset:14848
	ds_read_b32 v7, v20 offset:15104
	ds_read_b32 v8, v20 offset:15360
	ds_read_b32 v9, v20 offset:15616
	ds_read_b32 v10, v20 offset:15872
	ds_read_b32 v11, v20 offset:16128
	ds_read_b32 v12, v20 offset:22528
	ds_read_b32 v13, v20 offset:22784
	ds_read_b32 v14, v20 offset:23040
	ds_read_b32 v15, v20 offset:23296
	ds_read_b32 v16, v20 offset:23552
	ds_read_b32 v17, v20 offset:23808
	ds_read_b32 v18, v20 offset:24064
	ds_read_b32 v19, v20 offset:24320
	s_waitcnt lgkmcnt(0)
; __device__ __forceinline__ int crow(int r, int hi) { return (r & 3) + 8 * (r >> 2) + 4 * hi; }
; __device__ __forceinline__ void sample_task(const Prm& P, Ctx& C, int task) {
;     ...
; #pragma unroll
;         for (int dblk = 0; dblk < 2; ++dblk)
; #pragma unroll
;             for (int r = 0; r < 16; ++r) atomicAdd((float*)(oacc + (dblk * 16 + r) * 64 + lane), o[dblk][r]);
;         __syncthreads();
;         if (C.wave == 0) {
;             if (slot == ts) { const float gate = ((const float*)(P.ws + WS_G))[row * 24 + head * 3 + 0];
; #pragma unroll
;                 for (int dblk = 0; dblk < 2; ++dblk)
; #pragma unroll
;                     for (int r = 0; r < 16; ++r) ocs[g * 64 + 32 * dblk + crow(r, hi)] = oacc[(dblk * 16 + r) * 64 + lane] * gate; }
	v_add_f32_e32 v4, v4, v12
	v_add_f32_e32 v5, v5, v13
	v_add_f32_e32 v6, v6, v14
	v_add_f32_e32 v7, v7, v15
	v_add_f32_e32 v8, v8, v16
	v_add_f32_e32 v9, v9, v17
	v_add_f32_e32 v10, v10, v18
	v_add_f32_e32 v11, v11, v19
	ds_read_b32 v12, v20 offset:30720
	ds_read_b32 v13, v20 offset:30976
	ds_read_b32 v14, v20 offset:31232
	ds_read_b32 v15, v20 offset:31488
	ds_read_b32 v16, v20 offset:31744
	ds_read_b32 v17, v20 offset:32000
	ds_read_b32 v18, v20 offset:32256
	ds_read_b32 v19, v20 offset:32512
	s_waitcnt lgkmcnt(0)
	v_add_f32_e32 v4, v4, v12
	v_add_f32_e32 v5, v5, v13
	v_add_f32_e32 v6, v6, v14
	v_add_f32_e32 v7, v7, v15
	v_add_f32_e32 v8, v8, v16
	v_add_f32_e32 v9, v9, v17
	v_add_f32_e32 v10, v10, v18
	v_add_f32_e32 v11, v11, v19
	ds_read_b32 v12, v20 offset:38912
	ds_read_b32 v13, v20 offset:39168
	ds_read_b32 v14, v20 offset:39424
	ds_read_b32 v15, v20 offset:39680
	ds_read_b32 v16, v20 offset:39936
	ds_read_b32 v17, v20 offset:40192
	ds_read_b32 v18, v20 offset:40448
	ds_read_b32 v19, v20 offset:40704
	s_waitcnt lgkmcnt(0)
	v_add_f32_e32 v4, v4, v12
	v_add_f32_e32 v5, v5, v13
	v_add_f32_e32 v6, v6, v14
	v_add_f32_e32 v7, v7, v15
	v_add_f32_e32 v8, v8, v16
	v_add_f32_e32 v9, v9, v17
	v_add_f32_e32 v10, v10, v18
	v_add_f32_e32 v11, v11, v19
	ds_read_b32 v12, v21 offset:14336
	ds_read_b32 v13, v21 offset:14592
	ds_read_b32 v14, v21 offset:14848
	ds_read_b32 v15, v21 offset:15104
	ds_read_b32 v16, v21 offset:15360
	ds_read_b32 v17, v21 offset:15616
	ds_read_b32 v18, v21 offset:15872
	ds_read_b32 v19, v21 offset:16128
	s_waitcnt lgkmcnt(0)
	v_add_f32_e32 v4, v4, v12
	v_add_f32_e32 v5, v5, v13
	v_add_f32_e32 v6, v6, v14
	v_add_f32_e32 v7, v7, v15
	v_add_f32_e32 v8, v8, v16
	v_add_f32_e32 v9, v9, v17
	v_add_f32_e32 v10, v10, v18
	v_add_f32_e32 v11, v11, v19
	ds_read_b32 v12, v21 offset:22528
	ds_read_b32 v13, v21 offset:22784
	ds_read_b32 v14, v21 offset:23040
	ds_read_b32 v15, v21 offset:23296
	ds_read_b32 v16, v21 offset:23552
	ds_read_b32 v17, v21 offset:23808
	ds_read_b32 v18, v21 offset:24064
	ds_read_b32 v19, v21 offset:24320
	s_waitcnt lgkmcnt(0)
	v_add_f32_e32 v4, v4, v12
	v_add_f32_e32 v5, v5, v13
	v_add_f32_e32 v6, v6, v14
	v_add_f32_e32 v7, v7, v15
	v_add_f32_e32 v8, v8, v16
	v_add_f32_e32 v9, v9, v17
	v_add_f32_e32 v10, v10, v18
	v_add_f32_e32 v11, v11, v19
	ds_read_b32 v12, v21 offset:30720
	ds_read_b32 v13, v21 offset:30976
	ds_read_b32 v14, v21 offset:31232
	ds_read_b32 v15, v21 offset:31488
	ds_read_b32 v16, v21 offset:31744
	ds_read_b32 v17, v21 offset:32000
	ds_read_b32 v18, v21 offset:32256
	ds_read_b32 v19, v21 offset:32512
	s_waitcnt lgkmcnt(0)
	v_add_f32_e32 v4, v4, v12
	v_add_f32_e32 v5, v5, v13
	v_add_f32_e32 v6, v6, v14
	v_add_f32_e32 v7, v7, v15
	v_add_f32_e32 v8, v8, v16
	v_add_f32_e32 v9, v9, v17
	v_add_f32_e32 v10, v10, v18
	v_add_f32_e32 v11, v11, v19
	ds_read_b32 v12, v21 offset:38912
	ds_read_b32 v13, v21 offset:39168
	ds_read_b32 v14, v21 offset:39424
	ds_read_b32 v15, v21 offset:39680
	ds_read_b32 v16, v21 offset:39936
	ds_read_b32 v17, v21 offset:40192
	ds_read_b32 v18, v21 offset:40448
	ds_read_b32 v19, v21 offset:40704
	s_waitcnt lgkmcnt(0)
	v_add_f32_e32 v4, v4, v12
	v_add_f32_e32 v5, v5, v13
	v_add_f32_e32 v6, v6, v14
	v_add_f32_e32 v7, v7, v15
	v_add_f32_e32 v8, v8, v16
	v_add_f32_e32 v9, v9, v17
	v_add_f32_e32 v10, v10, v18
	v_add_f32_e32 v11, v11, v19
	v_mul_f32_e32 v4, v0, v4
	v_mul_f32_e32 v5, v0, v5
	v_mul_f32_e32 v6, v0, v6
	v_mul_f32_e32 v7, v0, v7
	v_mul_f32_e32 v8, v0, v8
	v_mul_f32_e32 v9, v0, v9
	v_mul_f32_e32 v10, v0, v10
	v_mul_f32_e32 v11, v0, v11
	ds_write_b32 v199, v4 offset:192
	ds_write_b32 v199, v5 offset:196
	ds_write_b32 v199, v6 offset:200
	ds_write_b32 v199, v7 offset:204
	ds_write_b32 v199, v8 offset:224
	ds_write_b32 v199, v9 offset:228
	ds_write_b32 v199, v10 offset:232
	ds_write_b32 v199, v11 offset:236

; #define LAS __attribute__((address_space(3)))
; template <int NBL>
; __device__ __forceinline__ unsigned topk_select(const LAS float* sc  , int sub, int cur) {
;     unsigned v[NBL]; unsigned candm = 0u, forced = 0u;
; #pragma unroll
;     for (int e = 0; e < NBL; ++e) { const int j = sub * NBL + e; const bool cand = (j >= 1) && (j <= cur - 2);
;         v[e] = cand ? __float_as_uint(sc[j]) : 0u; if (cand) candm |= 1u << e;
;         if (j == 0 || j == cur || (j == cur - 1 && cur >= 1)) forced |= 1u << e; }
;     const int nf = cur == 0 ? 1 : (cur == 1 ? 2 : 3), kk = 16 - nf, ncand = cur - 2 > 0 ? cur - 2 : 0;
;     unsigned prefix = 0u;
;     {
;         unsigned ceil_ = 0xFFFFFFFFu; int taken = 0; bool done = ncand <= kk;
; __device__ __forceinline__ void sample_task(const Prm& P, Ctx& C, int task) {
;     ...
;             const int slot2 = lane >> 3, sub = lane & 7;
;             const unsigned bits = topk_select<32>(sc + slot2 * 256, sub, 256);
.Lw0_topk:
	v_readlane_b32 s2, v250, 20
	v_readlane_b32 s3, v250, 21
	v_readlane_b32 s4, v253, 28
	v_readlane_b32 s5, v253, 29
	s_add_u32 s2, s2, s4
	s_addc_u32 s3, s3, s5
	v_readlane_b32 s4, v251, 55
	s_lshl_b32 s4, s4, 10
	s_add_u32 s2, s2, s4
	s_addc_u32 s3, s3, 0
	s_lshl_b32 s4, s33, 2
	s_add_u32 s2, s2, s4
	s_addc_u32 s3, s3, 0
	v_mbcnt_lo_u32_b32 v234, -1, 0
	v_mbcnt_hi_u32_b32 v234, -1, v234
	v_lshlrev_b32_e32 v234, 10, v234
	global_load_dword v236, v234, s[2:3]
	global_load_dword v237, v234, s[2:3] offset:128
	global_load_dword v238, v234, s[2:3] offset:512
	global_load_dword v239, v234, s[2:3] offset:640
	v_mov_b32_e32 v32, 0x7ffffffe
	v_mov_b32_e32 v0, 0
	v_mov_b32_e32 v34, 0
	s_mov_b64 s[0:1], exec
	v_readlane_b32 s2, v253, 13
	v_readlane_b32 s3, v253, 14
	s_and_b64 s[2:3], s[0:1], s[2:3]
	s_mov_b64 exec, s[2:3]
	ds_read_b32 v34, v189
	v_bfrev_b32_e32 v32, -2
	s_or_b64 exec, exec, s[0:1]
	ds_read2_b32 v[30:31], v189 offset0:1 offset1:2
	ds_read2_b32 v[28:29], v189 offset0:3 offset1:4
	ds_read2_b32 v[26:27], v189 offset0:5 offset1:6
	ds_read2_b32 v[24:25], v189 offset0:7 offset1:8
	ds_read2_b32 v[22:23], v189 offset0:9 offset1:10
	ds_read2_b32 v[20:21], v189 offset0:11 offset1:12
	ds_read2_b32 v[18:19], v189 offset0:13 offset1:14
	ds_read2_b32 v[16:17], v189 offset0:15 offset1:16
	ds_read2_b32 v[14:15], v189 offset0:17 offset1:18
	ds_read2_b32 v[12:13], v189 offset0:19 offset1:20
	ds_read2_b32 v[10:11], v189 offset0:21 offset1:22
	ds_read2_b32 v[8:9], v189 offset0:23 offset1:24
	ds_read2_b32 v[6:7], v189 offset0:25 offset1:26
	ds_read2_b32 v[4:5], v189 offset0:27 offset1:28
	ds_read2_b32 v[2:3], v189 offset0:29 offset1:30
	s_mov_b64 s[0:1], exec
	v_readlane_b32 s2, v253, 21
	v_readlane_b32 s3, v253, 22
	s_and_b64 s[2:3], s[0:1], s[2:3]
	v_readlane_b32 s8, v251, 2
	s_mov_b64 exec, s[2:3]
	ds_read_b32 v0, v189 offset:124
	v_or_b32_e32 v32, 0x80000000, v32
	s_or_b64 exec, exec, s[0:1]
	s_mov_b64 s[2:3], 0
	v_mov_b32_e32 v35, -1
	v_mov_b32_e32 v33, 0
	v_mov_b32_e32 v36, 14
	v_mov_b32_e32 v37, 0
	s_branch .LBB0_1535
